# P8a prompt path: per-fetch vmcnt(0) also dropped for the W=2 and W=4 column groups (same argument; CFG check shows only infeasible WAW paths)
# speedup vs baseline: 1.0241x; 1.0061x over previous
.LBB0_1664:
	s_andn2_b64 vcc, exec, s[10:11]
	s_cbranch_vccnz .LBB0_1667
	v_mov_b32_e32 v3, 0
	s_andn2_b64 vcc, exec, s[8:9]
	v_mov_b32_e32 v2, 0
	v_mov_b32_e32 v1, 0
	v_mov_b32_e32 v0, 0
	s_cbranch_vccnz .LBB0_1667
	s_and_b32 s8, s18, 0xfffff000
	s_add_i32 s8, s8, s19
	s_ashr_i32 s9, s8, 31
	s_lshl_b64 s[8:9], s[8:9], 13
	v_lshl_add_u64 v[0:1], v[86:87], 0, s[8:9]
	global_load_dwordx4 v[0:3], v[0:1], off
.LBB0_1667:
	s_add_i32 s19, s20, -6
	s_cmp_gt_u32 s20, 5
	s_cselect_b64 s[10:11], -1, 0
	s_cmp_lt_u32 s20, 6
	v_cndmask_b32_e64 v4, 0, 1, s[26:27]
	s_cselect_b64 s[52:53], -1, 0
	v_cmp_ne_u32_e64 s[8:9], 1, v4
	s_andn2_b64 vcc, exec, s[26:27]
	s_mov_b64 s[44:45], -1
	s_cbranch_vccnz .LBB0_1673
	s_andn2_b64 vcc, exec, s[52:53]
	s_cbranch_vccnz .LBB0_1670
	s_mul_i32 s44, s33, 15
	s_ashr_i32 s45, s44, 31
	s_add_i32 s52, s25, 9
	s_add_u32 s44, s44, s52
	s_addc_u32 s45, s45, 0
	s_lshl_b64 s[44:45], s[44:45], 13
	v_lshl_add_u64 v[4:5], v[84:85], 0, s[44:45]
	global_load_dwordx4 v[4:7], v[4:5], off
	s_mov_b64 s[44:45], 0

.LBB0_1673:
	s_andn2_b64 vcc, exec, s[44:45]
	s_cbranch_vccnz .LBB0_1676
	v_mov_b32_e32 v7, 0
	s_andn2_b64 vcc, exec, s[10:11]
	v_mov_b32_e32 v6, 0
	v_mov_b32_e32 v5, 0
	v_mov_b32_e32 v4, 0
	s_cbranch_vccnz .LBB0_1676
	s_and_b32 s10, s18, 0xfffff000
	s_add_i32 s10, s10, s19
	s_ashr_i32 s11, s10, 31
	s_lshl_b64 s[10:11], s[10:11], 13
	v_lshl_add_u64 v[4:5], v[86:87], 0, s[10:11]
	global_load_dwordx4 v[4:7], v[4:5], off

.LBB0_1682:
	s_andn2_b64 vcc, exec, s[44:45]
	s_cbranch_vccnz .LBB0_1685
	v_mov_b32_e32 v11, 0
	s_andn2_b64 vcc, exec, s[10:11]
	v_mov_b32_e32 v10, 0
	v_mov_b32_e32 v9, 0
	v_mov_b32_e32 v8, 0
	s_cbranch_vccnz .LBB0_1685
	s_and_b32 s10, s18, 0xfffff000
	s_add_i32 s10, s10, s19
	s_ashr_i32 s11, s10, 31
	s_lshl_b64 s[10:11], s[10:11], 13
	v_lshl_add_u64 v[8:9], v[86:87], 0, s[10:11]
	global_load_dwordx4 v[8:11], v[8:9], off

.LBB0_1699:
	s_andn2_b64 vcc, exec, s[8:9]
	s_cbranch_vccnz .LBB0_1702
	v_mov_b32_e32 v3, 0
	s_and_b64 vcc, exec, s[10:11]
	v_mov_b32_e32 v2, 0
	v_mov_b32_e32 v1, 0
	v_mov_b32_e32 v0, 0
	s_cbranch_vccnz .LBB0_1702
	s_and_b32 s8, s18, 0xfffff000
	s_add_i32 s8, s8, s19
	s_ashr_i32 s9, s8, 31
	s_lshl_b64 s[8:9], s[8:9], 13
	v_lshl_add_u64 v[0:1], v[86:87], 0, s[8:9]
	global_load_dwordx4 v[0:3], v[0:1], off

.LBB0_1708:
	s_andn2_b64 vcc, exec, s[44:45]
	s_cbranch_vccnz .LBB0_1711
	v_mov_b32_e32 v7, 0
	s_and_b64 vcc, exec, s[10:11]
	v_mov_b32_e32 v6, 0
	v_mov_b32_e32 v5, 0
	v_mov_b32_e32 v4, 0
	s_cbranch_vccnz .LBB0_1711
	s_and_b32 s44, s18, 0xfffff000
	s_add_i32 s44, s44, s19
	s_ashr_i32 s45, s44, 31
	s_lshl_b64 s[44:45], s[44:45], 13
	v_lshl_add_u64 v[4:5], v[86:87], 0, s[44:45]
	global_load_dwordx4 v[4:7], v[4:5], off

.LBB0_1717:
	s_andn2_b64 vcc, exec, s[44:45]
	s_cbranch_vccnz .LBB0_1720
	v_mov_b32_e32 v11, 0
	s_and_b64 vcc, exec, s[10:11]
	v_mov_b32_e32 v10, 0
	v_mov_b32_e32 v9, 0
	v_mov_b32_e32 v8, 0
	s_cbranch_vccnz .LBB0_1720
	s_and_b32 s10, s18, 0xfffff000
	s_add_i32 s10, s10, s19
	s_ashr_i32 s11, s10, 31
	s_lshl_b64 s[10:11], s[10:11], 13
	v_lshl_add_u64 v[8:9], v[86:87], 0, s[10:11]
	global_load_dwordx4 v[8:11], v[8:9], off
